# fnet2 tasks: input staging loops unrolled (8 row loads in flight, counted vmcnt) instead of 4 serialized load-wait-convert round trips
# speedup vs baseline: 1.0179x; 1.0179x over previous
.LBB0_557:
	s_lshl_b32 s48, s70, 1
	s_ashr_i32 s49, s48, 31
	s_lshl_b64 s[0:1], s[48:49], 16
	v_mov_b32_e32 v142, v132
	s_add_u32 s19, s0, 0xc000000
	s_addc_u32 s66, s1, 0
	v_cmp_gt_i32_e32 vcc, s29, v142
	s_and_saveexec_b64 s[0:1], vcc
	s_cbranch_execz .LBB0_560
	s_add_u32 s50, s4, s19
	s_addc_u32 s51, s5, s66
	s_add_u32 s62, s50, 0x10000
	s_addc_u32 s63, s51, 0
	v_lshlrev_b32_e32 v4, 4, v142
	v_lshlrev_b32_e32 v5, 1, v142
	v_and_b32_e32 v5, -8, v5
	v_lshl_add_u32 v5, v142, 6, v5
	global_load_dwordx4 v[64:67], v4, s[62:63] nt
	global_load_dwordx4 v[60:63], v4, s[50:51] nt
	v_add_u32_e32 v6, 0x2000, v4
	global_load_dwordx4 v[72:75], v6, s[62:63] nt
	global_load_dwordx4 v[68:71], v6, s[50:51] nt
	v_add_u32_e32 v7, 0x4000, v4
	global_load_dwordx4 v[80:83], v7, s[62:63] nt
	global_load_dwordx4 v[76:79], v7, s[50:51] nt
	v_add_u32_e32 v2, 0x6000, v4
	global_load_dwordx4 v[88:91], v2, s[62:63] nt
	global_load_dwordx4 v[84:87], v2, s[50:51] nt
	v_add_u32_e32 v40, 0x8400, v5
	v_add_u32_e32 v41, 0x10800, v5
	v_add_u32_e32 v42, 0x18c00, v5
	s_waitcnt vmcnt(6)
	v_lshlrev_b32_e32 v8, 16, v60
	v_lshlrev_b32_e32 v9, 16, v64
	v_and_b32_e32 v10, 0xffff0000, v60
	v_and_b32_e32 v11, 0xffff0000, v64
	v_lshlrev_b32_e32 v12, 16, v61
	v_lshlrev_b32_e32 v13, 16, v65
	v_and_b32_e32 v14, 0xffff0000, v61
	v_and_b32_e32 v15, 0xffff0000, v65
	v_lshlrev_b32_e32 v16, 16, v62
	v_lshlrev_b32_e32 v17, 16, v66
	v_and_b32_e32 v18, 0xffff0000, v62
	v_and_b32_e32 v19, 0xffff0000, v66
	v_lshlrev_b32_e32 v20, 16, v63
	v_lshlrev_b32_e32 v21, 16, v67
	v_and_b32_e32 v22, 0xffff0000, v63
	v_and_b32_e32 v23, 0xffff0000, v67
	ds_write2_b64 v5, v[8:9], v[10:11] offset0:0 offset1:1
	ds_write2_b64 v5, v[12:13], v[14:15] offset0:2 offset1:3
	ds_write2_b64 v5, v[16:17], v[18:19] offset0:4 offset1:5
	ds_write2_b64 v5, v[20:21], v[22:23] offset0:6 offset1:7
	s_waitcnt vmcnt(4)
	v_lshlrev_b32_e32 v24, 16, v68
	v_lshlrev_b32_e32 v25, 16, v72
	v_and_b32_e32 v26, 0xffff0000, v68
	v_and_b32_e32 v27, 0xffff0000, v72
	v_lshlrev_b32_e32 v28, 16, v69
	v_lshlrev_b32_e32 v29, 16, v73
	v_and_b32_e32 v30, 0xffff0000, v69
	v_and_b32_e32 v31, 0xffff0000, v73
	v_lshlrev_b32_e32 v32, 16, v70
	v_lshlrev_b32_e32 v33, 16, v74
	v_and_b32_e32 v34, 0xffff0000, v70
	v_and_b32_e32 v35, 0xffff0000, v74
	v_lshlrev_b32_e32 v36, 16, v71
	v_lshlrev_b32_e32 v37, 16, v75
	v_and_b32_e32 v38, 0xffff0000, v71
	v_and_b32_e32 v39, 0xffff0000, v75
	ds_write2_b64 v40, v[24:25], v[26:27] offset0:0 offset1:1
	ds_write2_b64 v40, v[28:29], v[30:31] offset0:2 offset1:3
	ds_write2_b64 v40, v[32:33], v[34:35] offset0:4 offset1:5
	ds_write2_b64 v40, v[36:37], v[38:39] offset0:6 offset1:7
	s_waitcnt vmcnt(2)
	v_lshlrev_b32_e32 v8, 16, v76
	v_lshlrev_b32_e32 v9, 16, v80
	v_and_b32_e32 v10, 0xffff0000, v76
	v_and_b32_e32 v11, 0xffff0000, v80
	v_lshlrev_b32_e32 v12, 16, v77
	v_lshlrev_b32_e32 v13, 16, v81
	v_and_b32_e32 v14, 0xffff0000, v77
	v_and_b32_e32 v15, 0xffff0000, v81
	v_lshlrev_b32_e32 v16, 16, v78
	v_lshlrev_b32_e32 v17, 16, v82
	v_and_b32_e32 v18, 0xffff0000, v78
	v_and_b32_e32 v19, 0xffff0000, v82
	v_lshlrev_b32_e32 v20, 16, v79
	v_lshlrev_b32_e32 v21, 16, v83
	v_and_b32_e32 v22, 0xffff0000, v79
	v_and_b32_e32 v23, 0xffff0000, v83
	ds_write2_b64 v41, v[8:9], v[10:11] offset0:0 offset1:1
	ds_write2_b64 v41, v[12:13], v[14:15] offset0:2 offset1:3
	ds_write2_b64 v41, v[16:17], v[18:19] offset0:4 offset1:5
	ds_write2_b64 v41, v[20:21], v[22:23] offset0:6 offset1:7
	s_waitcnt vmcnt(0)
	v_lshlrev_b32_e32 v24, 16, v84
	v_lshlrev_b32_e32 v25, 16, v88
	v_and_b32_e32 v26, 0xffff0000, v84
	v_and_b32_e32 v27, 0xffff0000, v88
	v_lshlrev_b32_e32 v28, 16, v85
	v_lshlrev_b32_e32 v29, 16, v89
	v_and_b32_e32 v30, 0xffff0000, v85
	v_and_b32_e32 v31, 0xffff0000, v89
	v_lshlrev_b32_e32 v32, 16, v86
	v_lshlrev_b32_e32 v33, 16, v90
	v_and_b32_e32 v34, 0xffff0000, v86
	v_and_b32_e32 v35, 0xffff0000, v90
	v_lshlrev_b32_e32 v36, 16, v87
	v_lshlrev_b32_e32 v37, 16, v91
	v_and_b32_e32 v38, 0xffff0000, v87
	v_and_b32_e32 v39, 0xffff0000, v91
	ds_write2_b64 v42, v[24:25], v[26:27] offset0:0 offset1:1
	ds_write2_b64 v42, v[28:29], v[30:31] offset0:2 offset1:3
	ds_write2_b64 v42, v[32:33], v[34:35] offset0:4 offset1:5
	ds_write2_b64 v42, v[36:37], v[38:39] offset0:6 offset1:7

.LBB0_569:
	s_or_b64 exec, exec, s[0:1]
	v_mov_b32_e32 v142, v132
	s_barrier
	s_nop 0
	v_cmp_gt_i32_e32 vcc, s35, v142
	s_and_saveexec_b64 s[0:1], vcc
	s_cbranch_execz .LBB0_574
	s_add_u32 s19, s56, s19
	s_addc_u32 s41, s57, s66
	s_add_u32 s50, s19, 0x8008000
	s_addc_u32 s51, s41, 0
	s_add_u32 s62, s19, 0x8018000
	s_addc_u32 s63, s41, 0
	v_lshlrev_b32_e32 v4, 4, v142
	v_lshlrev_b32_e32 v5, 1, v142
	v_and_b32_e32 v5, -8, v5
	v_lshl_add_u32 v5, v142, 6, v5
	global_load_dwordx4 v[64:67], v4, s[62:63] nt
	global_load_dwordx4 v[60:63], v4, s[50:51] nt
	v_add_u32_e32 v6, 0x2000, v4
	global_load_dwordx4 v[72:75], v6, s[62:63] nt
	global_load_dwordx4 v[68:71], v6, s[50:51] nt
	v_add_u32_e32 v7, 0x4000, v4
	global_load_dwordx4 v[80:83], v7, s[62:63] nt
	global_load_dwordx4 v[76:79], v7, s[50:51] nt
	v_add_u32_e32 v2, 0x6000, v4
	global_load_dwordx4 v[88:91], v2, s[62:63] nt
	global_load_dwordx4 v[84:87], v2, s[50:51] nt
	v_add_u32_e32 v40, 0x8400, v5
	v_add_u32_e32 v41, 0x10800, v5
	v_add_u32_e32 v42, 0x18c00, v5
	s_waitcnt vmcnt(6)
	v_lshlrev_b32_e32 v8, 16, v60
	v_lshlrev_b32_e32 v9, 16, v64
	v_and_b32_e32 v10, 0xffff0000, v60
	v_and_b32_e32 v11, 0xffff0000, v64
	v_lshlrev_b32_e32 v12, 16, v61
	v_lshlrev_b32_e32 v13, 16, v65
	v_and_b32_e32 v14, 0xffff0000, v61
	v_and_b32_e32 v15, 0xffff0000, v65
	v_lshlrev_b32_e32 v16, 16, v62
	v_lshlrev_b32_e32 v17, 16, v66
	v_and_b32_e32 v18, 0xffff0000, v62
	v_and_b32_e32 v19, 0xffff0000, v66
	v_lshlrev_b32_e32 v20, 16, v63
	v_lshlrev_b32_e32 v21, 16, v67
	v_and_b32_e32 v22, 0xffff0000, v63
	v_and_b32_e32 v23, 0xffff0000, v67
	ds_write2_b64 v5, v[8:9], v[10:11] offset0:0 offset1:1
	ds_write2_b64 v5, v[12:13], v[14:15] offset0:2 offset1:3
	ds_write2_b64 v5, v[16:17], v[18:19] offset0:4 offset1:5
	ds_write2_b64 v5, v[20:21], v[22:23] offset0:6 offset1:7
	s_waitcnt vmcnt(4)
	v_lshlrev_b32_e32 v24, 16, v68
	v_lshlrev_b32_e32 v25, 16, v72
	v_and_b32_e32 v26, 0xffff0000, v68
	v_and_b32_e32 v27, 0xffff0000, v72
	v_lshlrev_b32_e32 v28, 16, v69
	v_lshlrev_b32_e32 v29, 16, v73
	v_and_b32_e32 v30, 0xffff0000, v69
	v_and_b32_e32 v31, 0xffff0000, v73
	v_lshlrev_b32_e32 v32, 16, v70
	v_lshlrev_b32_e32 v33, 16, v74
	v_and_b32_e32 v34, 0xffff0000, v70
	v_and_b32_e32 v35, 0xffff0000, v74
	v_lshlrev_b32_e32 v36, 16, v71
	v_lshlrev_b32_e32 v37, 16, v75
	v_and_b32_e32 v38, 0xffff0000, v71
	v_and_b32_e32 v39, 0xffff0000, v75
	ds_write2_b64 v40, v[24:25], v[26:27] offset0:0 offset1:1
	ds_write2_b64 v40, v[28:29], v[30:31] offset0:2 offset1:3
	ds_write2_b64 v40, v[32:33], v[34:35] offset0:4 offset1:5
	ds_write2_b64 v40, v[36:37], v[38:39] offset0:6 offset1:7
	s_waitcnt vmcnt(2)
	v_lshlrev_b32_e32 v8, 16, v76
	v_lshlrev_b32_e32 v9, 16, v80
	v_and_b32_e32 v10, 0xffff0000, v76
	v_and_b32_e32 v11, 0xffff0000, v80
	v_lshlrev_b32_e32 v12, 16, v77
	v_lshlrev_b32_e32 v13, 16, v81
	v_and_b32_e32 v14, 0xffff0000, v77
	v_and_b32_e32 v15, 0xffff0000, v81
	v_lshlrev_b32_e32 v16, 16, v78
	v_lshlrev_b32_e32 v17, 16, v82
	v_and_b32_e32 v18, 0xffff0000, v78
	v_and_b32_e32 v19, 0xffff0000, v82
	v_lshlrev_b32_e32 v20, 16, v79
	v_lshlrev_b32_e32 v21, 16, v83
	v_and_b32_e32 v22, 0xffff0000, v79
	v_and_b32_e32 v23, 0xffff0000, v83
	ds_write2_b64 v41, v[8:9], v[10:11] offset0:0 offset1:1
	ds_write2_b64 v41, v[12:13], v[14:15] offset0:2 offset1:3
	ds_write2_b64 v41, v[16:17], v[18:19] offset0:4 offset1:5
	ds_write2_b64 v41, v[20:21], v[22:23] offset0:6 offset1:7
	s_waitcnt vmcnt(0)
	v_lshlrev_b32_e32 v24, 16, v84
	v_lshlrev_b32_e32 v25, 16, v88
	v_and_b32_e32 v26, 0xffff0000, v84
	v_and_b32_e32 v27, 0xffff0000, v88
	v_lshlrev_b32_e32 v28, 16, v85
	v_lshlrev_b32_e32 v29, 16, v89
	v_and_b32_e32 v30, 0xffff0000, v85
	v_and_b32_e32 v31, 0xffff0000, v89
	v_lshlrev_b32_e32 v32, 16, v86
	v_lshlrev_b32_e32 v33, 16, v90
	v_and_b32_e32 v34, 0xffff0000, v86
	v_and_b32_e32 v35, 0xffff0000, v90
	v_lshlrev_b32_e32 v36, 16, v87
	v_lshlrev_b32_e32 v37, 16, v91
	v_and_b32_e32 v38, 0xffff0000, v87
	v_and_b32_e32 v39, 0xffff0000, v91
	ds_write2_b64 v42, v[24:25], v[26:27] offset0:0 offset1:1
	ds_write2_b64 v42, v[28:29], v[30:31] offset0:2 offset1:3
	ds_write2_b64 v42, v[32:33], v[34:35] offset0:4 offset1:5
	ds_write2_b64 v42, v[36:37], v[38:39] offset0:6 offset1:7
